# baseline (speedup 1.0000x reference)
; __device__ __forceinline__ unsigned xb_ld(unsigned* p)              { return __hip_atomic_load(p, __ATOMIC_RELAXED, __HIP_MEMORY_SCOPE_AGENT); }
; __device__ __forceinline__ unsigned xb_add(unsigned* p, unsigned v) { return __hip_atomic_fetch_add(p, v, __ATOMIC_RELAXED, __HIP_MEMORY_SCOPE_AGENT); }
; #define XB_SPIN(cond, bar) do { unsigned _sp = 0; while (cond) { __builtin_amdgcn_s_sleep(1); \
;     if ((++_sp & 255u) == 0u) { if (xb_ld(&(bar)[XB_TMO])) break; if (_sp > XB_SPIN_CAP) { atomicAdd(&(bar)[XB_TMO], 1u); break; } } } } while (0)
;     ...
;     const unsigned G = gridDim.x * gridDim.y * gridDim.z;
;     const unsigned old = xb_add(&bar[XB_CNT], 1u), gen = old / G;
;     if (old + 1u == (gen + 1u) * G) xb_add(&bar[XB_GEN], 1u); else XB_SPIN(xb_ld(&bar[XB_GEN]) == gen, bar);
;     __threadfence();
;     unsigned nx = 0; for (unsigned j = 0; j < 16; ++j) nx += (xb_ld(&bar[XB_XCNT(j)]) > 0u);
;     st[0] = x; st[1] = xb_ld(&bar[XB_XCNT(x)]); st[2] = nx;
;   }
;   __syncthreads();
.LBB0_21:
	s_or_b64 exec, exec, s[12:13]
	v_mov_b32_e32 v1, 0xfc00000
	s_waitcnt vmcnt(0)
	global_load_dword v2, v1, s[8:9] offset:1024 sc1
	global_load_dword v3, v1, s[8:9] offset:1280 sc1
	global_load_dword v4, v1, s[8:9] offset:1536 sc1
	global_load_dword v5, v1, s[8:9] offset:1792 sc1
	global_load_dword v6, v1, s[8:9] offset:2048 sc1
	global_load_dword v7, v1, s[8:9] offset:2304 sc1
	global_load_dword v8, v1, s[8:9] offset:2560 sc1
	global_load_dword v9, v1, s[8:9] offset:2816 sc1
	global_load_dword v10, v1, s[8:9] offset:3072 sc1
	global_load_dword v11, v1, s[8:9] offset:3328 sc1
	global_load_dword v12, v1, s[8:9] offset:3584 sc1
	global_load_dword v13, v1, s[8:9] offset:3840 sc1
	v_mov_b32_e32 v1, 0xfc01000
	global_load_dword v14, v1, s[8:9] sc1
	global_load_dword v15, v1, s[8:9] offset:256 sc1
	global_load_dword v16, v1, s[8:9] offset:512 sc1
	s_mov_b32 s12, 0x20800
	v_mov_b32_e32 v19, s3
	s_add_i32 s3, s12, 0x100
	global_load_dword v1, v1, s[8:9] offset:768 sc1
	v_mov_b32_e32 v18, s3
	v_mov_b32_e32 v17, 0
	ds_write_b32 v18, v19
	global_load_dword v17, v17, s[10:11] offset:1024 sc1
	s_mov_b32 s3, 0x20804
	s_addk_i32 s3, 0x100
	v_mov_b32_e32 v18, s3
	v_mov_b64_e32 v[172:173], s[6:7]
	s_waitcnt vmcnt(16)
	v_cmp_ne_u32_e32 vcc, 0, v2
	s_nop 1
	v_cndmask_b32_e64 v2, 0, 1, vcc
	s_waitcnt vmcnt(14)
	v_cmp_ne_u32_e32 vcc, 0, v4
	s_nop 1
	v_cndmask_b32_e64 v4, 0, 1, vcc
	s_waitcnt vmcnt(12)
	v_cmp_ne_u32_e32 vcc, 0, v6
	s_nop 1
	v_cndmask_b32_e64 v6, 0, 1, vcc
	s_waitcnt vmcnt(10)
	v_cmp_ne_u32_e32 vcc, 0, v8
	s_nop 1
	v_cndmask_b32_e64 v8, 0, 1, vcc
	s_waitcnt vmcnt(8)
	v_cmp_ne_u32_e32 vcc, 0, v10
	s_nop 1
	v_cndmask_b32_e64 v10, 0, 1, vcc
	s_waitcnt vmcnt(6)
	v_cmp_ne_u32_e32 vcc, 0, v12
	s_nop 1
	v_cndmask_b32_e64 v12, 0, 1, vcc
	s_waitcnt vmcnt(4)
	v_cmp_ne_u32_e32 vcc, 0, v14
	s_nop 1
	v_cndmask_b32_e64 v14, 0, 1, vcc
	s_waitcnt vmcnt(2)
	v_cmp_ne_u32_e32 vcc, 0, v16
	s_nop 1
	v_cndmask_b32_e64 v16, 0, 1, vcc
	v_cmp_ne_u32_e32 vcc, 0, v3
	s_nop 1
	v_addc_co_u32_e32 v2, vcc, 0, v2, vcc
	v_cmp_ne_u32_e32 vcc, 0, v5
	s_nop 1
	v_addc_co_u32_e32 v2, vcc, v2, v4, vcc
	v_cmp_ne_u32_e32 vcc, 0, v7
	s_nop 1
	v_addc_co_u32_e32 v2, vcc, v2, v6, vcc
	v_cmp_ne_u32_e32 vcc, 0, v9
	s_nop 1
	v_addc_co_u32_e32 v2, vcc, v2, v8, vcc
	v_cmp_ne_u32_e32 vcc, 0, v11
	s_nop 1
	v_addc_co_u32_e32 v2, vcc, v2, v10, vcc
	v_cmp_ne_u32_e32 vcc, 0, v13
	s_nop 1
	v_addc_co_u32_e32 v2, vcc, v2, v12, vcc
	v_cmp_ne_u32_e32 vcc, 0, v15
	s_nop 1
	v_addc_co_u32_e32 v2, vcc, v2, v14, vcc
	s_waitcnt vmcnt(1)
	v_cmp_ne_u32_e32 vcc, 0, v1
	s_nop 1
	v_addc_co_u32_e32 v1, vcc, v2, v16, vcc
	s_waitcnt vmcnt(0)
	ds_write2_b32 v18, v17, v1 offset1:1
